# one-pass LRU: summary records self-validating (A preset to an invalid pattern in phase 2), no separate flags or publisher wait
# baseline (speedup 1.0000x reference)
; template <int PASS> __device__ void lru_phase(const Params& p, unsigned char* smem) {
;     ...
;     if ((int)blockIdx.x < 4096) LRU_CLOAD((int)blockIdx.x);
.LBB0_310:
	v_and_b32_e32 v70, 0x3ff, v0
	v_lshl_or_b32 v72, s70, 9, v70
	v_lshlrev_b32_e32 v72, 3, v72
	s_add_u32 s4, s64, 0x1f100000
	s_addc_u32 s5, s65, 0
	v_mov_b32_e32 v70, -1
	v_mov_b32_e32 v71, 0
	s_lshl_b32 s2, s62, 12
	s_mov_b32 s3, 0
LRUX_zloop:
	v_cmp_gt_u32_e32 vcc, 0x400000, v72
	s_and_saveexec_b64 s[6:7], vcc
	s_cbranch_execz LRUX_zdone
	global_store_dwordx2 v72, v[70:71], s[4:5] sc0 sc1
	v_add_u32_e32 v72, s2, v72
	s_or_b64 exec, exec, s[6:7]
	s_add_i32 s3, s3, 1
	s_cmp_lt_u32 s3, 64
	s_cbranch_scc1 LRUX_zloop
LRUX_zdone:
	s_or_b64 exec, exec, s[6:7]
	s_branch .LBB0_359
	s_add_u32 s0, s64, 0x4000000
	s_addc_u32 s1, s65, 0
	s_cmpk_lt_i32 s70, 0x1000
	s_cselect_b64 s[2:3], -1, 0
	s_cmpk_gt_i32 s70, 0xfff
	s_waitcnt lgkmcnt(0)
	v_readfirstlane_b32 s6, v1
	s_cbranch_scc1 .LBB0_320
	s_lshl_b32 s4, s70, 7
	v_lshlrev_b32_e32 v3, 3, v1
	s_and_b32 s4, s4, 0x780
	v_and_b32_e32 v3, 0x78, v3
	v_or_b32_e32 v3, s4, v3
	s_lshl_b32 s4, s70, 2
	v_lshrrev_b32_e32 v2, 4, v1
	s_and_b32 s5, s4, 0xfc0
	v_or_b32_e32 v14, s5, v2
	v_lshlrev_b32_e32 v2, 1, v3
	v_mov_b32_e32 v3, 0
	v_mov_b32_e32 v4, v3
	v_mov_b32_e32 v5, v3
	v_add_u32_e32 v15, -3, v14
	v_lshl_add_u64 v[30:31], s[0:1], 0, v[2:3]
	v_mov_b32_e32 v2, v3
	s_waitcnt vmcnt(0)
	v_mov_b64_e32 v[8:9], v[4:5]
	s_and_b32 s7, s4, 0xfffff000
	v_cmp_lt_i32_e32 vcc, -1, v15
	v_mov_b64_e32 v[6:7], v[2:3]
	s_and_saveexec_b64 s[4:5], vcc
	s_cbranch_execz .LBB0_313
	v_add_u32_e32 v6, s7, v15
	v_ashrrev_i32_e32 v7, 31, v6
	v_lshlrev_b64 v[6:7], 12, v[6:7]
	v_lshl_add_u64 v[6:7], v[30:31], 0, v[6:7]
	global_load_dwordx4 v[6:9], v[6:7], off

; __device__ __forceinline__ float softplusf_(float x) { return fmaxf(x, 0.f) + log1pf(__expf(-fabsf(x))); }
; __device__ __forceinline__ float fsig0(float x) { return __builtin_amdgcn_rcpf(1.0f + __expf(-x)); }
; template <int PASS> __device__ void lru_phase(const Params& p, unsigned char* smem) {
;     ...
;         {
;             const int ch = 16 * wave + (lane & 15), cgl = jb * 128 + ch;
;             const float ba_ = jb_fixed ? hb_a : p.in[6][cgl], bx_ = jb_fixed ? hb_x : p.in[8][cgl], sp = jb_fixed ? hsp : softplusf_(-p.in[9][cgl]);
; #pragma unroll
;             for (int m = 0; m < 4; ++m)
; #pragma unroll
;                 for (int r = 0; r < 4; ++r) { const int t = 16 * m + 4 * (lane >> 4) + r;
;                     const float rg = fsig0(accA[m][r] + ba_), ig = fsig0(accX[m][r] + bx_);
;                     const float la = -8.0f * rg * sp, a = __expf(la), u = __builtin_amdgcn_sqrtf(fmaxf(1.0f - a * a, 0.f)) * (ig * xcf[t * 132 + ch]);
;                     As[t * 132 + ch] = a; Us[t * 132 + ch] = u; }
.LBB0_572:
	s_waitcnt vmcnt(0)
	v_add_f32_e32 v66, v96, v100
	v_add_f32_e32 v96, v97, v100
	v_mul_f32_e32 v96, 0xbfb8aa3b, v96
	v_exp_f32_e32 v96, v96
	v_mul_f32_e32 v66, 0xbfb8aa3b, v66
	v_exp_f32_e32 v66, v66
	v_add_f32_e32 v93, v93, v101
	v_add_f32_e32 v96, 1.0, v96
	v_rcp_f32_e32 v96, v96
	v_add_f32_e32 v66, 1.0, v66
	v_mul_f32_e32 v93, 0xbfb8aa3b, v93
	v_rcp_f32_e32 v66, v66
	v_mul_f32_e32 v96, 0xc1000000, v96
	v_mul_f32_e32 v96, v96, v102
	v_mul_f32_e32 v96, 0x3fb8aa3b, v96
	v_exp_f32_e32 v93, v93
	v_exp_f32_e32 v96, v96
	ds_read2_b32 v[104:105], v141 offset1:132
	v_mul_f32_e32 v66, 0xc1000000, v66
	v_add_f32_e32 v93, 1.0, v93
	v_fma_f32 v103, -v96, v96, 1.0
	v_mul_f32_e32 v66, v66, v102
	v_rcp_f32_e32 v93, v93
	v_max_f32_e32 v103, 0, v103
	v_add_f32_e32 v98, v98, v100
	v_mul_f32_e32 v66, 0x3fb8aa3b, v66
	v_sqrt_f32_e32 v103, v103
	v_mul_f32_e32 v98, 0xbfb8aa3b, v98
	v_exp_f32_e32 v66, v66
	v_exp_f32_e32 v98, v98
	s_waitcnt lgkmcnt(0)
	v_mul_f32_e32 v93, v93, v105
	v_mul_f32_e32 v93, v93, v103
	v_add_u32_e32 v103, 0x8400, v141
	v_fma_f32 v97, -v66, v66, 1.0
	ds_write2_b32 v103, v66, v96 offset1:132
	v_add_f32_e32 v66, 1.0, v98
	v_rcp_f32_e32 v66, v66
	v_add_f32_e32 v94, v94, v101
	v_add_f32_e32 v98, v99, v100
	v_mul_f32_e32 v94, 0xbfb8aa3b, v94
	v_mul_f32_e32 v66, 0xc1000000, v66
	v_mul_f32_e32 v66, v66, v102
	v_mul_f32_e32 v66, 0x3fb8aa3b, v66
	v_mul_f32_e32 v98, 0xbfb8aa3b, v98
	v_exp_f32_e32 v94, v94
	v_exp_f32_e32 v66, v66
	v_exp_f32_e32 v98, v98
	ds_write_b32 v143, v93
	v_add_f32_e32 v93, 1.0, v94
	v_fma_f32 v94, -v66, v66, 1.0
	ds_read_b32 v96, v141 offset:1056
	ds_write_b32 v141, v66 offset:34848
	v_add_f32_e32 v66, 1.0, v98
	v_rcp_f32_e32 v93, v93
	v_max_f32_e32 v94, 0, v94
	v_rcp_f32_e32 v66, v66
	v_sqrt_f32_e32 v94, v94
	s_waitcnt lgkmcnt(1)
	v_mul_f32_e32 v93, v93, v96
	v_add_f32_e32 v88, v88, v100
	v_mul_f32_e32 v66, 0xc1000000, v66
	v_mul_f32_e32 v93, v94, v93
	v_add_f32_e32 v94, v95, v101
	v_mul_f32_e32 v66, v66, v102
	v_mul_f32_e32 v94, 0xbfb8aa3b, v94
	v_mul_f32_e32 v66, 0x3fb8aa3b, v66
	v_mul_f32_e32 v88, 0xbfb8aa3b, v88
	v_exp_f32_e32 v94, v94
	v_exp_f32_e32 v66, v66
	v_exp_f32_e32 v88, v88
	ds_write_b32 v144, v93
	v_add_f32_e32 v93, 1.0, v94
	v_fma_f32 v94, -v66, v66, 1.0
	ds_write_b32 v141, v66 offset:35376
	v_add_f32_e32 v66, 1.0, v88
	v_rcp_f32_e32 v66, v66
	ds_read_b32 v95, v141 offset:1584
	v_rcp_f32_e32 v93, v93
	v_max_f32_e32 v94, 0, v94
	v_mul_f32_e32 v66, 0xc1000000, v66
	v_mul_f32_e32 v66, v66, v102
	v_add_f32_e32 v89, v89, v100
	v_sqrt_f32_e32 v94, v94
	v_mul_f32_e32 v66, 0x3fb8aa3b, v66
	v_mul_f32_e32 v89, 0xbfb8aa3b, v89
	v_exp_f32_e32 v66, v66
	v_exp_f32_e32 v89, v89
	s_waitcnt lgkmcnt(0)
	v_mul_f32_e32 v93, v93, v95
	v_add_f32_e32 v84, v84, v101
	v_mul_f32_e32 v93, v94, v93
	v_mul_f32_e32 v84, 0xbfb8aa3b, v84
	v_exp_f32_e32 v84, v84
	ds_write_b32 v145, v93
	v_fma_f32 v88, -v66, v66, 1.0
	ds_write_b32 v141, v66 offset:42240
	v_add_f32_e32 v66, 1.0, v89
	v_rcp_f32_e32 v66, v66
	v_add_f32_e32 v84, 1.0, v84
	ds_read_b32 v93, v141 offset:8448
	v_rcp_f32_e32 v84, v84
	v_max_f32_e32 v88, 0, v88
	v_mul_f32_e32 v66, 0xc1000000, v66
	v_sqrt_f32_e32 v88, v88
	v_add_f32_e32 v85, v85, v101
	v_mul_f32_e32 v66, v66, v102
	v_add_f32_e32 v89, v90, v100
	v_mul_f32_e32 v85, 0xbfb8aa3b, v85
	v_mul_f32_e32 v66, 0x3fb8aa3b, v66
	v_mul_f32_e32 v89, 0xbfb8aa3b, v89
	v_exp_f32_e32 v85, v85
	v_exp_f32_e32 v66, v66
	v_exp_f32_e32 v89, v89
	s_waitcnt lgkmcnt(0)
	v_mul_f32_e32 v84, v84, v93
	v_mul_f32_e32 v84, v88, v84
	ds_write_b32 v146, v84
	v_add_f32_e32 v84, 1.0, v85
	v_fma_f32 v85, -v66, v66, 1.0
	ds_read_b32 v88, v141 offset:8976
	ds_write_b32 v141, v66 offset:42768
	v_add_f32_e32 v66, 1.0, v89
	v_rcp_f32_e32 v84, v84
	v_max_f32_e32 v85, 0, v85
	v_rcp_f32_e32 v66, v66
	v_sqrt_f32_e32 v85, v85
	s_waitcnt lgkmcnt(1)
	v_mul_f32_e32 v84, v84, v88
	v_add_f32_e32 v88, v91, v100
	v_mul_f32_e32 v66, 0xc1000000, v66
	v_mul_f32_e32 v84, v85, v84
	v_add_f32_e32 v85, v86, v101
	v_mul_f32_e32 v66, v66, v102
	v_mul_f32_e32 v85, 0xbfb8aa3b, v85
	v_mul_f32_e32 v66, 0x3fb8aa3b, v66
	v_mul_f32_e32 v88, 0xbfb8aa3b, v88
	v_exp_f32_e32 v85, v85
	v_exp_f32_e32 v66, v66
	v_exp_f32_e32 v88, v88
	ds_write_b32 v147, v84
	v_add_f32_e32 v84, 1.0, v85
	v_fma_f32 v85, -v66, v66, 1.0
	ds_read_b32 v86, v141 offset:9504
	ds_write_b32 v141, v66 offset:43296
	v_add_f32_e32 v66, 1.0, v88
	v_rcp_f32_e32 v84, v84
	v_max_f32_e32 v85, 0, v85
	v_rcp_f32_e32 v66, v66
	v_sqrt_f32_e32 v85, v85
	s_waitcnt lgkmcnt(1)
	v_mul_f32_e32 v84, v84, v86
	v_add_f32_e32 v80, v80, v100
	v_mul_f32_e32 v66, 0xc1000000, v66
	v_mul_f32_e32 v84, v85, v84
	v_add_f32_e32 v85, v87, v101
	v_mul_f32_e32 v66, v66, v102
	v_mul_f32_e32 v85, 0xbfb8aa3b, v85
	v_mul_f32_e32 v66, 0x3fb8aa3b, v66
	v_mul_f32_e32 v80, 0xbfb8aa3b, v80
	v_exp_f32_e32 v85, v85
	v_exp_f32_e32 v66, v66
	v_exp_f32_e32 v80, v80
	ds_write_b32 v148, v84
	v_add_f32_e32 v84, 1.0, v85
	v_fma_f32 v85, -v66, v66, 1.0
	ds_write_b32 v141, v66 offset:43824
	v_add_f32_e32 v66, 1.0, v80
	v_rcp_f32_e32 v66, v66
	ds_read_b32 v86, v141 offset:10032
	v_rcp_f32_e32 v84, v84
	v_max_f32_e32 v85, 0, v85
	v_mul_f32_e32 v66, 0xc1000000, v66
	v_mul_f32_e32 v66, v66, v102
	v_add_f32_e32 v81, v81, v100
	v_sqrt_f32_e32 v85, v85
	v_mul_f32_e32 v66, 0x3fb8aa3b, v66
	v_mul_f32_e32 v81, 0xbfb8aa3b, v81
	v_exp_f32_e32 v66, v66
	v_exp_f32_e32 v81, v81
	s_waitcnt lgkmcnt(0)
; __device__ __forceinline__ float softplusf_(float x) { return fmaxf(x, 0.f) + log1pf(__expf(-fabsf(x))); }
; #define LBAR0() do { asm volatile("s_waitcnt lgkmcnt(0)" ::: "memory"); __builtin_amdgcn_s_barrier(); asm volatile("" ::: "memory"); } while (0)
; __device__ __forceinline__ float fsig0(float x) { return __builtin_amdgcn_rcpf(1.0f + __expf(-x)); }
; template <int PASS> __device__ void lru_phase(const Params& p, unsigned char* smem) {
;     ...
;         {
;             const int ch = 16 * wave + (lane & 15), cgl = jb * 128 + ch;
;             const float ba_ = jb_fixed ? hb_a : p.in[6][cgl], bx_ = jb_fixed ? hb_x : p.in[8][cgl], sp = jb_fixed ? hsp : softplusf_(-p.in[9][cgl]);
; #pragma unroll
;             for (int m = 0; m < 4; ++m)
; #pragma unroll
;                 for (int r = 0; r < 4; ++r) { const int t = 16 * m + 4 * (lane >> 4) + r;
;                     const float rg = fsig0(accA[m][r] + ba_), ig = fsig0(accX[m][r] + bx_);
;                     const float la = -8.0f * rg * sp, a = __expf(la), u = __builtin_amdgcn_sqrtf(fmaxf(1.0f - a * a, 0.f)) * (ig * xcf[t * 132 + ch]);
;                     As[t * 132 + ch] = a; Us[t * 132 + ch] = u; }
;         }
;         LBAR0();
	v_mul_f32_e32 v84, v84, v86
	v_add_f32_e32 v76, v76, v101
	v_mul_f32_e32 v84, v85, v84
	v_mul_f32_e32 v76, 0xbfb8aa3b, v76
	v_exp_f32_e32 v76, v76
	ds_write_b32 v149, v84
	v_fma_f32 v80, -v66, v66, 1.0
	ds_write_b32 v141, v66 offset:50688
	v_add_f32_e32 v66, 1.0, v81
	v_rcp_f32_e32 v66, v66
	v_add_f32_e32 v76, 1.0, v76
	ds_read_b32 v84, v141 offset:16896
	v_rcp_f32_e32 v76, v76
	v_max_f32_e32 v80, 0, v80
	v_mul_f32_e32 v66, 0xc1000000, v66
	v_sqrt_f32_e32 v80, v80
	v_add_f32_e32 v77, v77, v101
	v_mul_f32_e32 v66, v66, v102
	v_add_f32_e32 v81, v82, v100
	v_mul_f32_e32 v77, 0xbfb8aa3b, v77
	v_mul_f32_e32 v66, 0x3fb8aa3b, v66
	v_mul_f32_e32 v81, 0xbfb8aa3b, v81
	v_exp_f32_e32 v77, v77
	v_exp_f32_e32 v66, v66
	v_exp_f32_e32 v81, v81
	s_waitcnt lgkmcnt(0)
	v_mul_f32_e32 v76, v76, v84
	v_mul_f32_e32 v76, v80, v76
	ds_write_b32 v150, v76
	v_add_f32_e32 v76, 1.0, v77
	v_fma_f32 v77, -v66, v66, 1.0
	ds_read_b32 v80, v141 offset:17424
	ds_write_b32 v141, v66 offset:51216
	v_add_f32_e32 v66, 1.0, v81
	v_rcp_f32_e32 v76, v76
	v_max_f32_e32 v77, 0, v77
	v_rcp_f32_e32 v66, v66
	v_sqrt_f32_e32 v77, v77
	s_waitcnt lgkmcnt(1)
	v_mul_f32_e32 v76, v76, v80
	v_add_f32_e32 v80, v83, v100
	v_mul_f32_e32 v66, 0xc1000000, v66
	v_mul_f32_e32 v76, v77, v76
	v_add_f32_e32 v77, v78, v101
	v_mul_f32_e32 v66, v66, v102
	v_mul_f32_e32 v77, 0xbfb8aa3b, v77
	v_mul_f32_e32 v66, 0x3fb8aa3b, v66
	v_mul_f32_e32 v80, 0xbfb8aa3b, v80
	v_exp_f32_e32 v77, v77
	v_exp_f32_e32 v66, v66
	v_exp_f32_e32 v80, v80
	ds_write_b32 v151, v76
	v_add_f32_e32 v76, 1.0, v77
	v_fma_f32 v77, -v66, v66, 1.0
	ds_read_b32 v78, v141 offset:17952
	ds_write_b32 v141, v66 offset:51744
	v_add_f32_e32 v66, 1.0, v80
	v_rcp_f32_e32 v76, v76
	v_max_f32_e32 v77, 0, v77
	v_rcp_f32_e32 v66, v66
	v_sqrt_f32_e32 v77, v77
	s_waitcnt lgkmcnt(1)
	v_mul_f32_e32 v76, v76, v78
	v_add_f32_e32 v72, v72, v100
	v_mul_f32_e32 v66, 0xc1000000, v66
	v_mul_f32_e32 v76, v77, v76
	v_add_f32_e32 v77, v79, v101
	v_mul_f32_e32 v66, v66, v102
	v_mul_f32_e32 v77, 0xbfb8aa3b, v77
	v_mul_f32_e32 v66, 0x3fb8aa3b, v66
	v_mul_f32_e32 v72, 0xbfb8aa3b, v72
	v_exp_f32_e32 v77, v77
	v_exp_f32_e32 v66, v66
	v_exp_f32_e32 v72, v72
	ds_write_b32 v152, v76
	v_add_f32_e32 v76, 1.0, v77
	v_fma_f32 v77, -v66, v66, 1.0
	ds_write_b32 v141, v66 offset:52272
	v_add_f32_e32 v66, 1.0, v72
	v_rcp_f32_e32 v66, v66
	ds_read_b32 v78, v141 offset:18480
	v_rcp_f32_e32 v76, v76
	v_max_f32_e32 v77, 0, v77
	v_mul_f32_e32 v66, 0xc1000000, v66
	v_mul_f32_e32 v66, v66, v102
	v_add_f32_e32 v73, v73, v100
	v_sqrt_f32_e32 v77, v77
	v_mul_f32_e32 v66, 0x3fb8aa3b, v66
	v_mul_f32_e32 v73, 0xbfb8aa3b, v73
	v_exp_f32_e32 v66, v66
	v_exp_f32_e32 v73, v73
	s_waitcnt lgkmcnt(0)
	v_mul_f32_e32 v76, v76, v78
	v_add_f32_e32 v68, v68, v101
	v_mul_f32_e32 v76, v77, v76
	v_mul_f32_e32 v68, 0xbfb8aa3b, v68
	v_exp_f32_e32 v68, v68
	ds_write_b32 v153, v76
	v_fma_f32 v72, -v66, v66, 1.0
	ds_write_b32 v141, v66 offset:59136
	v_add_f32_e32 v66, 1.0, v73
	v_rcp_f32_e32 v66, v66
	v_add_f32_e32 v68, 1.0, v68
	ds_read_b32 v76, v141 offset:25344
	v_rcp_f32_e32 v68, v68
	v_max_f32_e32 v72, 0, v72
	v_mul_f32_e32 v66, 0xc1000000, v66
	v_sqrt_f32_e32 v72, v72
	v_add_f32_e32 v69, v69, v101
	v_mul_f32_e32 v66, v66, v102
	v_add_f32_e32 v73, v74, v100
	v_mul_f32_e32 v69, 0xbfb8aa3b, v69
	v_mul_f32_e32 v66, 0x3fb8aa3b, v66
	v_mul_f32_e32 v73, 0xbfb8aa3b, v73
	v_exp_f32_e32 v69, v69
	v_exp_f32_e32 v66, v66
	v_exp_f32_e32 v73, v73
	s_waitcnt lgkmcnt(0)
	v_mul_f32_e32 v68, v68, v76
	v_mul_f32_e32 v68, v72, v68
	ds_write_b32 v154, v68
	v_add_f32_e32 v68, 1.0, v69
	v_fma_f32 v69, -v66, v66, 1.0
	ds_read_b32 v72, v141 offset:25872
	ds_write_b32 v141, v66 offset:59664
	v_add_f32_e32 v66, 1.0, v73
	v_rcp_f32_e32 v68, v68
	v_max_f32_e32 v69, 0, v69
	v_rcp_f32_e32 v66, v66
	v_sqrt_f32_e32 v69, v69
	s_waitcnt lgkmcnt(1)
	v_mul_f32_e32 v68, v68, v72
	v_add_f32_e32 v72, v75, v100
	v_mul_f32_e32 v66, 0xc1000000, v66
	v_mul_f32_e32 v68, v69, v68
	v_add_f32_e32 v69, v70, v101
	v_mul_f32_e32 v66, v66, v102
	v_mul_f32_e32 v69, 0xbfb8aa3b, v69
	v_mul_f32_e32 v66, 0x3fb8aa3b, v66
	v_mul_f32_e32 v72, 0xbfb8aa3b, v72
	v_exp_f32_e32 v69, v69
	v_exp_f32_e32 v66, v66
	v_exp_f32_e32 v72, v72
	ds_write_b32 v155, v68
	v_add_f32_e32 v68, 1.0, v69
	v_fma_f32 v69, -v66, v66, 1.0
	ds_read_b32 v70, v141 offset:26400
	ds_write_b32 v141, v66 offset:60192
	v_add_f32_e32 v66, 1.0, v72
	v_rcp_f32_e32 v68, v68
	v_max_f32_e32 v69, 0, v69
	v_rcp_f32_e32 v66, v66
	v_sqrt_f32_e32 v69, v69
	v_add_f32_e32 v92, v92, v101
	s_waitcnt lgkmcnt(1)
	v_mul_f32_e32 v68, v68, v70
	v_mul_f32_e32 v66, 0xc1000000, v66
	v_mul_f32_e32 v92, 0xbfb8aa3b, v92
	v_mul_f32_e32 v68, v69, v68
	v_add_f32_e32 v69, v71, v101
	v_mul_f32_e32 v66, v66, v102
	v_exp_f32_e32 v92, v92
	v_mul_f32_e32 v69, 0xbfb8aa3b, v69
	v_mul_f32_e32 v66, 0x3fb8aa3b, v66
	v_exp_f32_e32 v69, v69
	v_exp_f32_e32 v66, v66
	v_add_f32_e32 v92, 1.0, v92
	ds_write_b32 v156, v68
	v_rcp_f32_e32 v92, v92
	v_max_f32_e32 v97, 0, v97
	v_add_f32_e32 v68, 1.0, v69
	v_fma_f32 v69, -v66, v66, 1.0
	ds_read_b32 v70, v141 offset:26928
	v_sqrt_f32_e32 v97, v97
	v_rcp_f32_e32 v68, v68
	v_max_f32_e32 v69, 0, v69
	v_sqrt_f32_e32 v69, v69
	v_mul_f32_e32 v92, v92, v104
	v_mul_f32_e32 v71, v92, v97
	s_waitcnt lgkmcnt(0)
	v_mul_f32_e32 v68, v68, v70
	ds_write_b32 v142, v71
	v_mul_f32_e32 v68, v69, v68
	ds_write_b32 v141, v66 offset:60720
	ds_write_b32 v157, v68
	s_waitcnt lgkmcnt(0)
	s_barrier
; #define LBAR0() do { asm volatile("s_waitcnt lgkmcnt(0)" ::: "memory"); __builtin_amdgcn_s_barrier(); asm volatile("" ::: "memory"); } while (0)
; template <int PASS> __device__ void lru_phase(const Params& p, unsigned char* smem) {
;     ...
;         { float h = 0.f, A = 1.f;
; #pragma unroll
;           for (int tt = 0; tt < 16; ++tt) { const int t = q * 16 + tt; const float a = As[t * 132 + ch], u = Us[t * 132 + ch]; h = a * h + u; A *= a;
;               if (PASS == 2) { Us[t * 132 + ch] = h; As[t * 132 + ch] = A; } }
;           qA[q * 128 + ch] = A; qH[q * 128 + ch] = h; }
;         LBAR0();
;         if (PASS == 1) {
;             if (q == 0) { float h = 0.f, A = 1.f;
; #pragma unroll
;                 for (int qq = 0; qq < 4; ++qq) { h = qA[qq * 128 + ch] * h + qH[qq * 128 + ch]; A *= qA[qq * 128 + ch]; }
;                 LA[(size_t)(b * 64 + c) * 2048 + cgl] = A; LH[(size_t)(b * 64 + c) * 2048 + cgl] = h; }
	ds_read_b32 v66, v158 offset:33792
	ds_read_b32 v68, v1
	s_lshl_b32 s4, s25, 6
	s_or_b32 s4, s4, s24
	s_ashr_i32 s5, s4, 31
	s_lshl_b64 s[4:5], s[4:5], 13
	s_waitcnt lgkmcnt(0)
	v_fmac_f32_e32 v68, 0, v66
	ds_write_b32 v1, v68
	ds_read_b32 v69, v160 offset:33792
	ds_read_b32 v70, v161
	s_add_u32 s4, s26, s4
	s_addc_u32 s5, s27, s5
	s_waitcnt lgkmcnt(1)
	v_mul_f32_e32 v66, v66, v69
	s_waitcnt lgkmcnt(0)
	v_fmac_f32_e32 v70, v68, v69
	ds_write_b32 v161, v70
	ds_write_b32 v160, v66 offset:33792
	ds_read_b32 v68, v163 offset:33792
	ds_read_b32 v69, v164
	s_waitcnt lgkmcnt(1)
	v_mul_f32_e32 v66, v66, v68
	s_waitcnt lgkmcnt(0)
	v_fmac_f32_e32 v69, v70, v68
	ds_write_b32 v164, v69
	ds_write_b32 v163, v66 offset:33792
	ds_read_b32 v68, v166 offset:33792
	ds_read_b32 v70, v167
	s_waitcnt lgkmcnt(1)
	v_mul_f32_e32 v66, v66, v68
	s_waitcnt lgkmcnt(0)
	v_fmac_f32_e32 v70, v69, v68
	ds_write_b32 v167, v70
	ds_write_b32 v166, v66 offset:33792
	ds_read_b32 v68, v169 offset:33792
	ds_read_b32 v69, v170
	s_waitcnt lgkmcnt(1)
	v_mul_f32_e32 v66, v66, v68
	s_waitcnt lgkmcnt(0)
	v_fmac_f32_e32 v69, v70, v68
	ds_write_b32 v170, v69
	ds_write_b32 v169, v66 offset:33792
	ds_read_b32 v68, v172 offset:33792
	ds_read_b32 v70, v173
	s_waitcnt lgkmcnt(1)
	v_mul_f32_e32 v66, v66, v68
	s_waitcnt lgkmcnt(0)
	v_fmac_f32_e32 v70, v69, v68
	ds_write_b32 v173, v70
	ds_write_b32 v172, v66 offset:33792
	ds_read_b32 v68, v175 offset:33792
	ds_read_b32 v69, v176
	s_waitcnt lgkmcnt(1)
	v_mul_f32_e32 v66, v66, v68
	s_waitcnt lgkmcnt(0)
	v_fmac_f32_e32 v69, v70, v68
	ds_write_b32 v176, v69
	ds_write_b32 v175, v66 offset:33792
	ds_read_b32 v68, v178 offset:33792
	ds_read_b32 v70, v179
	s_waitcnt lgkmcnt(1)
	v_mul_f32_e32 v66, v66, v68
	s_waitcnt lgkmcnt(0)
	v_fmac_f32_e32 v70, v69, v68
	ds_write_b32 v179, v70
	ds_write_b32 v178, v66 offset:33792
	ds_read_b32 v68, v181 offset:33792
	ds_read_b32 v69, v182
	s_waitcnt lgkmcnt(1)
	v_mul_f32_e32 v66, v66, v68
	s_waitcnt lgkmcnt(0)
	v_fmac_f32_e32 v69, v70, v68
	ds_write_b32 v182, v69
	ds_write_b32 v181, v66 offset:33792
	ds_read_b32 v68, v184 offset:33792
	ds_read_b32 v70, v185
	s_waitcnt lgkmcnt(1)
	v_mul_f32_e32 v66, v66, v68
	s_waitcnt lgkmcnt(0)
	v_fmac_f32_e32 v70, v69, v68
	ds_write_b32 v185, v70
	ds_write_b32 v184, v66 offset:33792
	ds_read_b32 v68, v187 offset:33792
	ds_read_b32 v69, v188
	s_waitcnt lgkmcnt(1)
	v_mul_f32_e32 v66, v66, v68
	s_waitcnt lgkmcnt(0)
	v_fmac_f32_e32 v69, v70, v68
	ds_write_b32 v188, v69
	ds_write_b32 v187, v66 offset:33792
	ds_read_b32 v68, v190 offset:33792
	ds_read_b32 v70, v191
	s_waitcnt lgkmcnt(1)
	v_mul_f32_e32 v66, v66, v68
	s_waitcnt lgkmcnt(0)
	v_fmac_f32_e32 v70, v69, v68
	ds_write_b32 v191, v70
	ds_write_b32 v190, v66 offset:33792
	ds_read_b32 v68, v193 offset:33792
	ds_read_b32 v69, v194
	s_waitcnt lgkmcnt(1)
	v_mul_f32_e32 v66, v66, v68
	s_waitcnt lgkmcnt(0)
	v_fmac_f32_e32 v69, v70, v68
	ds_write_b32 v194, v69
	ds_write_b32 v193, v66 offset:33792
	ds_read_b32 v68, v196 offset:33792
	ds_read_b32 v70, v197
	s_waitcnt lgkmcnt(1)
	v_mul_f32_e32 v66, v66, v68
	s_waitcnt lgkmcnt(0)
	v_fmac_f32_e32 v70, v69, v68
	ds_write_b32 v197, v70
	ds_write_b32 v196, v66 offset:33792
	ds_read_b32 v68, v199 offset:33792
	ds_read_b32 v69, v200
	s_waitcnt lgkmcnt(1)
	v_mul_f32_e32 v66, v66, v68
	s_waitcnt lgkmcnt(0)
	v_fmac_f32_e32 v69, v70, v68
	ds_write_b32 v200, v69
	ds_write_b32 v199, v66 offset:33792
	ds_read_b32 v68, v202 offset:33792
	ds_read_b32 v70, v203
	s_waitcnt lgkmcnt(0)
	v_fmac_f32_e32 v70, v69, v68
	v_mul_f32_e32 v68, v66, v68
	ds_write_b32 v203, v70
	ds_write_b32 v202, v68 offset:33792
	v_or_b32_e32 v66, s39, v132
	ds_write_b32 v139, v68
	ds_write_b32 v140, v70
	s_waitcnt lgkmcnt(0)
	s_barrier
	v_lshlrev_b32_e32 v68, 2, v66
	v_bfe_u32 v85, v0, 6, 3
	s_sub_i32 s40, s37, s62
	s_bfe_u32 s41, s40, 0x60004
	s_lshr_b32 s42, s40, 10
	s_nop 0
	v_readfirstlane_b32 s47, v85
	s_lshl_b32 s44, s42, 6
	s_or_b32 s44, s44, s41
	s_cmp_lt_u32 s47, 2
	s_cbranch_scc0 LRUX_join
	s_add_u32 s48, s64, 0x1f100000
	s_addc_u32 s49, s65, 0
	v_add_u32_e32 v71, 0xfffff800, v205
	ds_read_b32 v72, v71
	ds_read_b32 v73, v71 offset:512
	ds_read_b32 v74, v71 offset:1024
	ds_read_b32 v75, v71 offset:1536
	ds_read_b32 v76, v71 offset:2048
	ds_read_b32 v77, v71 offset:2560
	ds_read_b32 v78, v71 offset:3072
	ds_read_b32 v79, v71 offset:3584
	s_lshl_b32 s45, s44, 14
	v_lshl_add_u32 v82, v66, 3, s45
	s_waitcnt lgkmcnt(0)
	v_fma_f32 v81, v73, v76, v77
	v_mul_f32_e32 v80, v72, v73
	v_fma_f32 v81, v74, v81, v78
	v_mul_f32_e32 v80, v80, v74
	v_fma_f32 v81, v75, v81, v79
	v_mul_f32_e32 v80, v80, v75
	global_store_dwordx2 v82, v[80:81], s[48:49] sc0 sc1
	s_cmp_lt_u32 s41, 16
	s_cbranch_scc0 LRUX_keepP
	v_mov_b32_e32 v252, 0
; template <int PASS> __device__ void lru_phase(const Params& p, unsigned char* smem) {
;     ...
;             if (q == 0) { float h = 0.f, A = 1.f;
; #pragma unroll
;                 for (int qq = 0; qq < 4; ++qq) { h = qA[qq * 128 + ch] * h + qH[qq * 128 + ch]; A *= qA[qq * 128 + ch]; }
;                 LA[(size_t)(b * 64 + c) * 2048 + cgl] = A; LH[(size_t)(b * 64 + c) * 2048 + cgl] = h; }
;         } else {
;             float carry = LC[(size_t)(b * 64 + c) * 2048 + cgl];
;             for (int qq = 0; qq < q; ++qq) carry = qA[qq * 128 + ch] * carry + qH[qq * 128 + ch];
LRUX_keepP:
	s_cmp_eq_u32 s41, 0
	s_cbranch_scc1 LRUX_polled
	s_movk_i32 s59, 0x400
LRUX_poll:
	v_mov_b32_e32 v86, 0
	s_cmp_lt_u32 s41, 1
	s_cbranch_scc1 LRUX_ld1
	v_add_u32_e32 v87, 0xffffc000, v82
	global_load_dwordx2 v[98:99], v87, s[48:49] sc0 sc1
LRUX_ld1:
	s_cmp_lt_u32 s41, 2
	s_cbranch_scc1 LRUX_ld2
	v_add_u32_e32 v87, 0xffff8000, v82
	global_load_dwordx2 v[100:101], v87, s[48:49] sc0 sc1
LRUX_ld2:
	s_cmp_lt_u32 s41, 3
	s_cbranch_scc1 LRUX_ld3
	v_add_u32_e32 v87, 0xffff4000, v82
	global_load_dwordx2 v[102:103], v87, s[48:49] sc0 sc1
LRUX_ld3:
	s_cmp_lt_u32 s41, 4
	s_cbranch_scc1 LRUX_ld4
	v_add_u32_e32 v87, 0xffff0000, v82
	global_load_dwordx2 v[104:105], v87, s[48:49] sc0 sc1
LRUX_ld4:
	s_cmp_lt_u32 s41, 5
	s_cbranch_scc1 LRUX_ld5
	v_add_u32_e32 v87, 0xfffec000, v82
	global_load_dwordx2 v[106:107], v87, s[48:49] sc0 sc1
LRUX_ld5:
	s_cmp_lt_u32 s41, 6
	s_cbranch_scc1 LRUX_ld6
	v_add_u32_e32 v87, 0xfffe8000, v82
	global_load_dwordx2 v[108:109], v87, s[48:49] sc0 sc1
LRUX_ld6:
	s_cmp_lt_u32 s41, 7
	s_cbranch_scc1 LRUX_ld7
	v_add_u32_e32 v87, 0xfffe4000, v82
	global_load_dwordx2 v[110:111], v87, s[48:49] sc0 sc1
LRUX_ld7:
	s_cmp_lt_u32 s41, 8
	s_cbranch_scc1 LRUX_ld8
	v_add_u32_e32 v87, 0xfffe0000, v82
	global_load_dwordx2 v[112:113], v87, s[48:49] sc0 sc1
LRUX_ld8:
	s_cmp_lt_u32 s41, 9
	s_cbranch_scc1 LRUX_ld9
	v_add_u32_e32 v87, 0xfffdc000, v82
	global_load_dwordx2 v[114:115], v87, s[48:49] sc0 sc1
LRUX_ld9:
	s_cmp_lt_u32 s41, 10
	s_cbranch_scc1 LRUX_ld10
	v_add_u32_e32 v87, 0xfffd8000, v82
	global_load_dwordx2 v[116:117], v87, s[48:49] sc0 sc1
LRUX_ld10:
	s_cmp_lt_u32 s41, 11
	s_cbranch_scc1 LRUX_ld11
	v_add_u32_e32 v87, 0xfffd4000, v82
	global_load_dwordx2 v[118:119], v87, s[48:49] sc0 sc1
LRUX_ld11:
	s_cmp_lt_u32 s41, 12
	s_cbranch_scc1 LRUX_ld12
	v_add_u32_e32 v87, 0xfffd0000, v82
	global_load_dwordx2 v[120:121], v87, s[48:49] sc0 sc1
LRUX_ld12:
	s_cmp_lt_u32 s41, 13
	s_cbranch_scc1 LRUX_ld13
	v_add_u32_e32 v87, 0xfffcc000, v82
	global_load_dwordx2 v[122:123], v87, s[48:49] sc0 sc1
LRUX_ld13:
	s_cmp_lt_u32 s41, 14
	s_cbranch_scc1 LRUX_ld14
	v_add_u32_e32 v87, 0xfffc8000, v82
	global_load_dwordx2 v[228:229], v87, s[48:49] sc0 sc1
LRUX_ld14:
	s_cmp_lt_u32 s41, 15
	s_cbranch_scc1 LRUX_ld15
	v_add_u32_e32 v87, 0xfffc4000, v82
	global_load_dwordx2 v[230:231], v87, s[48:49] sc0 sc1
LRUX_ld15:
	s_waitcnt vmcnt(0)
	s_cmp_lt_u32 s41, 1
	s_cbranch_scc1 LRUX_mx1
	v_max_u32_e32 v86, v86, v98
LRUX_mx1:
	s_cmp_lt_u32 s41, 2
	s_cbranch_scc1 LRUX_mx2
	v_max_u32_e32 v86, v86, v100
LRUX_mx2:
	s_cmp_lt_u32 s41, 3
	s_cbranch_scc1 LRUX_mx3
	v_max_u32_e32 v86, v86, v102
LRUX_mx3:
	s_cmp_lt_u32 s41, 4
	s_cbranch_scc1 LRUX_mx4
	v_max_u32_e32 v86, v86, v104
LRUX_mx4:
	s_cmp_lt_u32 s41, 5
	s_cbranch_scc1 LRUX_mx5
	v_max_u32_e32 v86, v86, v106
LRUX_mx5:
	s_cmp_lt_u32 s41, 6
	s_cbranch_scc1 LRUX_mx6
	v_max_u32_e32 v86, v86, v108
LRUX_mx6:
	s_cmp_lt_u32 s41, 7
	s_cbranch_scc1 LRUX_mx7
	v_max_u32_e32 v86, v86, v110
LRUX_mx7:
	s_cmp_lt_u32 s41, 8
	s_cbranch_scc1 LRUX_mx8
	v_max_u32_e32 v86, v86, v112
LRUX_mx8:
	s_cmp_lt_u32 s41, 9
	s_cbranch_scc1 LRUX_mx9
	v_max_u32_e32 v86, v86, v114
LRUX_mx9:
	s_cmp_lt_u32 s41, 10
	s_cbranch_scc1 LRUX_mx10
	v_max_u32_e32 v86, v86, v116
LRUX_mx10:
	s_cmp_lt_u32 s41, 11
	s_cbranch_scc1 LRUX_mx11
	v_max_u32_e32 v86, v86, v118
LRUX_mx11:
	s_cmp_lt_u32 s41, 12
	s_cbranch_scc1 LRUX_mx12
	v_max_u32_e32 v86, v86, v120
LRUX_mx12:
	s_cmp_lt_u32 s41, 13
	s_cbranch_scc1 LRUX_mx13
	v_max_u32_e32 v86, v86, v122
LRUX_mx13:
	s_cmp_lt_u32 s41, 14
	s_cbranch_scc1 LRUX_mx14
	v_max_u32_e32 v86, v86, v228
LRUX_mx14:
	s_cmp_lt_u32 s41, 15
	s_cbranch_scc1 LRUX_mx15
	v_max_u32_e32 v86, v86, v230
LRUX_mx15:
	v_cmp_eq_u32_e32 vcc, -1, v86
	s_cbranch_vccz LRUX_polled
	s_add_i32 s59, s59, -1
	s_cmp_eq_u32 s59, 0
	s_cbranch_scc1 LRUX_polled
	s_sleep 1
	s_branch LRUX_poll
LRUX_polled:
	v_mov_b32_e32 v70, v252
	s_cmp_lt_u32 s41, 15
	s_cbranch_scc1 LRUX_sk15
	v_fma_f32 v70, v230, v70, v231
